# strategy 4: attention inner loop with one static s_setprio 1 for waves 4-7 and all per-segment flips removed
# baseline (speedup 1.0000x reference)
.LBB0_201:
	s_or_b64 exec, exec, s[6:7]
	v_mov_b32_e32 v0, s97
	s_waitcnt lgkmcnt(0)
	s_barrier
	ds_read_b32 v0, v0
	s_movk_i32 s6, 0x17f
	s_waitcnt lgkmcnt(0)
	s_barrier
	v_cmp_lt_u32_e32 vcc, s6, v0
	v_readfirstlane_b32 s4, v0
	s_mov_b64 s[6:7], -1
	s_cbranch_vccnz .LBB0_196
	s_add_i32 s4, s4, s26
	s_and_b32 s6, s4, 0xffff
	s_mul_i32 s6, s6, 0xaaab
	s_lshr_b32 s8, s6, 20
	s_mul_i32 s6, s8, 24
	s_sub_i32 s9, s4, s6
	s_mul_i32 s4, s9, 0xab
	s_lshl_b32 s7, s8, 7
	s_bfe_u32 s4, s4, 0x6000a
	v_subrev_u32_e32 v26, s7, v199
	s_mul_i32 s6, s4, 6
	v_add_u32_e32 v212, 0xf80, v26
	s_sub_i32 s6, s9, s6
	v_or_b32_e32 v213, v212, v181
	s_lshl_b32 s7, s4, 12
	v_add_lshl_u32 v160, v213, s7, 11
	s_and_b32 s10, s6, 0xff
	v_lshl_add_u64 v[0:1], s[64:65], 0, v[160:161]
	s_lshl_b32 s4, s10, 8
	v_lshl_add_u64 v[0:1], v[0:1], 0, s[4:5]
	v_lshl_add_u64 v[0:1], v[176:177], 1, v[0:1]
	v_mov_b32_e32 v189, v161
	v_lshl_add_u64 v[24:25], v[0:1], 0, v[188:189]
	v_add_u32_e32 v2, s7, v200
	v_mov_b64_e32 v[0:1], s[30:31]
	v_mad_i64_i32 v[0:1], s[6:7], v2, s35, v[0:1]
	v_lshl_add_u64 v[0:1], v[0:1], 0, s[4:5]
	s_lshl_b32 s4, s9, 7
	v_mov_b32_e32 v191, v161
	s_and_b32 s4, s4, 0xff80
	v_lshl_add_u64 v[194:195], v[0:1], 0, v[190:191]
	v_lshl_add_u64 v[0:1], s[4:5], 0, v[178:179]
	s_mov_b32 s4, 0xc000
	v_lshlrev_b64 v[0:1], 13, v[0:1]
	v_add_co_u32_e32 v8, vcc, s4, v194
	v_lshl_add_u64 v[196:197], v[182:183], 0, v[0:1]
	s_nop 0
	v_addc_co_u32_e32 v9, vcc, 0, v195, vcc
	s_mov_b32 s4, 0x80000
	v_add_co_u32_e32 v12, vcc, s4, v196
	s_mov_b32 s4, 0x18000
	s_nop 0
	v_addc_co_u32_e32 v13, vcc, 0, v197, vcc
	global_load_dwordx4 v[0:3], v[194:195], off
	global_load_dwordx4 v[4:7], v[196:197], off
	s_nop 0
	global_load_dwordx4 v[8:11], v[8:9], off
	s_nop 0
	global_load_dwordx4 v[12:15], v[12:13], off
	v_add_co_u32_e32 v16, vcc, s4, v194
	s_mov_b32 s4, 0x24000
	s_nop 0
	v_addc_co_u32_e32 v17, vcc, 0, v195, vcc
	v_add_co_u32_e32 v20, vcc, s4, v194
	s_mov_b32 s24, 1
	s_nop 0
	v_addc_co_u32_e32 v21, vcc, 0, v195, vcc
	global_load_dwordx4 v[16:19], v[16:17], off
	s_nop 0
	global_load_dwordx4 v[20:23], v[20:21], off
	s_nop 0
	global_load_dwordx4 v[128:131], v[24:25], off
	global_load_dwordx4 v[132:135], v[24:25], off offset:32
	global_load_dwordx4 v[136:139], v[24:25], off offset:64
	global_load_dwordx4 v[140:143], v[24:25], off offset:96
	v_add_u32_e32 v189, 0xc800, v211
	v_add_u32_e32 v191, 0xf000, v211
	s_lshl_b32 s27, s10, 7
	s_lshl_b32 s22, s8, 1
	s_waitcnt vmcnt(9)
	ds_write_b128 v175, v[0:3]
	s_waitcnt vmcnt(7)
	ds_write_b128 v175, v[8:11] offset:8704
	ds_write2_b64 v189, v[4:5], v[6:7] offset0:128 offset1:130
	s_waitcnt vmcnt(6)
	ds_write2_b64 v191, v[12:13], v[14:15] offset1:2
	s_waitcnt vmcnt(5)
	ds_write_b128 v175, v[16:19] offset:17408
	s_waitcnt vmcnt(4)
	ds_write_b128 v175, v[20:23] offset:26112
	s_waitcnt lgkmcnt(0)
	s_barrier
	s_setprio 1
	v_add_u32_e32 v8, v203, v204
	ds_read_b128 v[0:3], v8
	ds_read_b128 v[4:7], v8 offset:32
	s_mov_b32 s4, s5
	s_mov_b32 s6, s5
	s_mov_b32 s7, s5
	s_waitcnt vmcnt(3) lgkmcnt(1)
	v_mfma_f32_32x32x16_bf16 v[64:79], v[0:3], v[128:131], 0
	s_mov_b32 s8, s5
	s_mov_b32 s9, s5
	s_mov_b32 s10, s5
	s_mov_b32 s11, s5
	s_mov_b32 s12, s5
	s_mov_b32 s13, s5
	s_mov_b32 s14, s5
	s_waitcnt vmcnt(2) lgkmcnt(0)
	v_mfma_f32_32x32x16_bf16 v[64:79], v[4:7], v[132:135], v[64:79]
	ds_read_b128 v[0:3], v8 offset:64
	ds_read_b128 v[4:7], v8 offset:96
	s_mov_b32 s15, s5
	s_mov_b32 s16, s5
	s_mov_b32 s17, s5
	s_mov_b32 s18, s5
	s_mov_b32 s19, s5
	s_waitcnt vmcnt(1) lgkmcnt(1)
	v_mfma_f32_32x32x16_bf16 v[64:79], v[0:3], v[136:139], v[64:79]
	s_waitcnt vmcnt(0) lgkmcnt(0)
	v_mfma_f32_32x32x16_bf16 v[64:79], v[4:7], v[140:143], v[64:79]
	ds_read_b128 v[0:3], v8 offset:8704
	ds_read_b128 v[4:7], v8 offset:8736
	ds_read_b128 v[16:19], v8 offset:8800
	s_waitcnt lgkmcnt(2)
	v_mfma_f32_32x32x16_bf16 v[80:95], v[0:3], v[128:131], 0
	ds_read_b128 v[0:3], v8 offset:8768
	s_waitcnt lgkmcnt(2)
	v_mfma_f32_32x32x16_bf16 v[80:95], v[4:7], v[132:135], v[80:95]
	s_waitcnt lgkmcnt(0)
	v_mfma_f32_32x32x16_bf16 v[80:95], v[0:3], v[136:139], v[80:95]
	v_mov_b64_e32 v[0:1], s[4:5]
	v_mov_b64_e32 v[2:3], s[6:7]
	v_mov_b64_e32 v[4:5], s[8:9]
	v_mov_b64_e32 v[6:7], s[10:11]
	v_mov_b64_e32 v[8:9], s[12:13]
	v_mov_b64_e32 v[10:11], s[14:15]
	v_mov_b64_e32 v[12:13], s[16:17]
	v_mfma_f32_32x32x16_bf16 v[80:95], v[16:19], v[140:143], v[80:95]
	v_mov_b64_e32 v[14:15], s[18:19]
	s_sub_i32 s12, 64, s22
	s_setprio 0
	v_add_u32_e32 v214, 0xf9f, v26
	v_mov_b64_e32 v[30:31], v[14:15]
	v_mov_b64_e32 v[46:47], v[14:15]
	v_mov_b64_e32 v[62:63], v[14:15]
	s_mov_b32 s13, 63
	s_sub_i32 s14, 63, s22
	s_mov_b32 s16, 2
	v_mov_b32_e32 v170, 0xff800000
	v_mov_b32_e32 v215, 0
	s_mov_b32 s15, 3
	v_mov_b64_e32 v[28:29], v[12:13]
	v_mov_b64_e32 v[26:27], v[10:11]
	v_mov_b64_e32 v[24:25], v[8:9]
	v_mov_b64_e32 v[22:23], v[6:7]
	v_mov_b64_e32 v[20:21], v[4:5]
	v_mov_b64_e32 v[18:19], v[2:3]
	v_mov_b64_e32 v[16:17], v[0:1]
	v_mov_b64_e32 v[44:45], v[12:13]
	v_mov_b64_e32 v[42:43], v[10:11]
	v_mov_b64_e32 v[40:41], v[8:9]
	v_mov_b64_e32 v[38:39], v[6:7]
	v_mov_b64_e32 v[36:37], v[4:5]
	v_mov_b64_e32 v[34:35], v[2:3]
	v_mov_b64_e32 v[32:33], v[0:1]
	v_mov_b64_e32 v[60:61], v[12:13]
	v_mov_b64_e32 v[58:59], v[10:11]
	v_mov_b64_e32 v[56:57], v[8:9]
	v_mov_b64_e32 v[54:55], v[6:7]
	v_mov_b64_e32 v[52:53], v[4:5]
	v_mov_b64_e32 v[50:51], v[2:3]
	v_mov_b64_e32 v[48:49], v[0:1]
	v_readlane_b32 s98, v253, 8
	s_cmp_lt_u32 s98, 4
	s_cbranch_scc1 .Lda_prio_skip
	s_setprio 1

.LBB0_203:
	v_sub_f32_e32 v103, v103, v234
	v_sub_f32_e32 v102, v102, v234
	v_sub_f32_e32 v101, v101, v234
	v_sub_f32_e32 v100, v100, v234
	v_sub_f32_e32 v99, v99, v234
	v_sub_f32_e32 v98, v98, v234
	v_sub_f32_e32 v97, v97, v234
	v_sub_f32_e32 v96, v96, v234
	v_sub_f32_e32 v119, v119, v234
	v_sub_f32_e32 v118, v118, v234
	v_sub_f32_e32 v117, v117, v234
	v_sub_f32_e32 v116, v116, v234
	v_sub_f32_e32 v115, v115, v234
	v_sub_f32_e32 v114, v114, v234
	v_sub_f32_e32 v113, v113, v234
	v_sub_f32_e32 v112, v112, v234
	v_sub_f32_e32 v107, v107, v234
	v_sub_f32_e32 v106, v106, v234
	v_sub_f32_e32 v105, v105, v234
	v_sub_f32_e32 v104, v104, v234
	v_sub_f32_e32 v123, v123, v234
	v_sub_f32_e32 v122, v122, v234
	v_sub_f32_e32 v121, v121, v234
	v_sub_f32_e32 v120, v120, v234
	v_exp_f32_e32 v96, v96
	v_exp_f32_e32 v97, v97
	v_exp_f32_e32 v98, v98
	v_exp_f32_e32 v99, v99
	v_exp_f32_e32 v100, v100
	v_exp_f32_e32 v101, v101
	v_exp_f32_e32 v102, v102
	v_exp_f32_e32 v103, v103
	v_exp_f32_e32 v112, v112
	v_exp_f32_e32 v113, v113
	v_exp_f32_e32 v114, v114
	v_exp_f32_e32 v115, v115
	v_exp_f32_e32 v116, v116
	v_exp_f32_e32 v117, v117
	v_exp_f32_e32 v118, v118
	v_exp_f32_e32 v119, v119
	v_sub_f32_e32 v111, v111, v234
	v_sub_f32_e32 v110, v110, v234
	v_sub_f32_e32 v109, v109, v234
	v_sub_f32_e32 v108, v108, v234
	v_sub_f32_e32 v127, v127, v234
	v_sub_f32_e32 v126, v126, v234
	v_sub_f32_e32 v125, v125, v234
	v_sub_f32_e32 v124, v124, v234
	v_exp_f32_e32 v104, v104
	v_exp_f32_e32 v105, v105
	v_exp_f32_e32 v106, v106
	v_exp_f32_e32 v107, v107
	v_exp_f32_e32 v120, v120
	v_exp_f32_e32 v122, v122
	v_exp_f32_e32 v123, v123
	v_exp_f32_e32 v121, v121
	v_exp_f32_e32 v108, v108
	v_exp_f32_e32 v109, v109
	v_exp_f32_e32 v110, v110
	v_exp_f32_e32 v111, v111
	v_exp_f32_e32 v124, v124
	v_exp_f32_e32 v125, v125
	v_exp_f32_e32 v126, v126
	v_exp_f32_e32 v127, v127
	v_pk_add_f32 v[226:227], v[100:101], v[116:117]
	v_pk_add_f32 v[236:237], v[96:97], v[112:113]
	v_pk_add_f32 v[238:239], v[102:103], v[118:119]
	v_pk_add_f32 v[240:241], v[98:99], v[114:115]
	v_pk_add_f32 v[222:223], v[106:107], v[122:123]
	v_pk_add_f32 v[224:225], v[104:105], v[120:121]
	v_pk_add_f32 v[238:239], v[240:241], v[238:239]
	v_pk_add_f32 v[226:227], v[236:237], v[226:227]
	v_pk_add_f32 v[162:163], v[108:109], v[124:125]
	v_pk_add_f32 v[164:165], v[110:111], v[126:127]
	v_pk_add_f32 v[224:225], v[224:225], v[226:227]
	v_pk_add_f32 v[222:223], v[222:223], v[238:239]
	v_pk_add_f32 v[162:163], v[162:163], v[224:225]
	v_pk_add_f32 v[164:165], v[164:165], v[222:223]
	v_add_f32_e32 v162, v162, v163
	v_add_f32_e32 v163, v164, v165
	v_add_f32_e32 v162, v162, v163
	v_fmac_f32_e32 v162, v215, v170
	ds_read_b128 v[222:225], v209
	ds_read_b128 v[240:243], v209 offset:4608
	ds_read_b128 v[244:247], v209 offset:9216
	ds_read_b128 v[248:251], v209 offset:13824
	v_cvt_pk_bf16_f32 v236, v96, v97
	v_cvt_pk_bf16_f32 v237, v98, v99
	v_cvt_pk_bf16_f32 v238, v100, v101
	v_cvt_pk_bf16_f32 v239, v102, v103
	s_waitcnt lgkmcnt(3)
	s_nop 0
	v_mfma_f32_32x32x16_bf16 v[48:63], v[222:225], v[236:239], v[48:63]
	ds_read_b128 v[222:225], v209 offset:32
	s_waitcnt lgkmcnt(3)
	v_mfma_f32_32x32x16_bf16 v[32:47], v[240:243], v[236:239], v[32:47]
	ds_read_b128 v[240:243], v209 offset:4640
	s_waitcnt lgkmcnt(3)
	v_mfma_f32_32x32x16_bf16 v[16:31], v[244:247], v[236:239], v[16:31]
	ds_read_b128 v[244:247], v209 offset:9248
	s_waitcnt lgkmcnt(3)
	v_mfma_f32_32x32x16_bf16 v[0:15], v[248:251], v[236:239], v[0:15]
	ds_read_b128 v[248:251], v209 offset:13856
	v_cvt_pk_bf16_f32 v236, v104, v105
	v_cvt_pk_bf16_f32 v237, v106, v107
	v_cvt_pk_bf16_f32 v238, v108, v109
	v_cvt_pk_bf16_f32 v239, v110, v111
	s_waitcnt lgkmcnt(3)
	s_nop 0
	v_mfma_f32_32x32x16_bf16 v[48:63], v[222:225], v[236:239], v[48:63]
	ds_read_b128 v[222:225], v209 offset:64
	s_waitcnt lgkmcnt(3)
	v_mfma_f32_32x32x16_bf16 v[32:47], v[240:243], v[236:239], v[32:47]
	ds_read_b128 v[240:243], v209 offset:4672
	s_waitcnt lgkmcnt(3)
	v_mfma_f32_32x32x16_bf16 v[16:31], v[244:247], v[236:239], v[16:31]
	ds_read_b128 v[244:247], v209 offset:9280
	s_waitcnt lgkmcnt(3)
	v_mfma_f32_32x32x16_bf16 v[0:15], v[248:251], v[236:239], v[0:15]
	ds_read_b128 v[248:251], v209 offset:13888
	v_cvt_pk_bf16_f32 v236, v112, v113
	v_cvt_pk_bf16_f32 v237, v114, v115
	v_cvt_pk_bf16_f32 v238, v116, v117
	v_cvt_pk_bf16_f32 v239, v118, v119
	s_waitcnt lgkmcnt(3)
	s_nop 0
	v_mfma_f32_32x32x16_bf16 v[48:63], v[222:225], v[236:239], v[48:63]
	ds_read_b128 v[222:225], v209 offset:96
	s_waitcnt lgkmcnt(3)
	v_mfma_f32_32x32x16_bf16 v[32:47], v[240:243], v[236:239], v[32:47]
	ds_read_b128 v[240:243], v209 offset:4704
	s_waitcnt lgkmcnt(3)
	v_mfma_f32_32x32x16_bf16 v[16:31], v[244:247], v[236:239], v[16:31]
	ds_read_b128 v[244:247], v209 offset:9312
	s_waitcnt lgkmcnt(3)
	v_mfma_f32_32x32x16_bf16 v[0:15], v[248:251], v[236:239], v[0:15]
	ds_read_b128 v[248:251], v209 offset:13920
	v_cvt_pk_bf16_f32 v236, v120, v121
	v_cvt_pk_bf16_f32 v237, v122, v123
	v_cvt_pk_bf16_f32 v238, v124, v125
	v_cvt_pk_bf16_f32 v239, v126, v127
	s_waitcnt lgkmcnt(3)
	s_nop 0
	v_mfma_f32_32x32x16_bf16 v[48:63], v[222:225], v[236:239], v[48:63]
	s_waitcnt lgkmcnt(2)
	v_mfma_f32_32x32x16_bf16 v[32:47], v[240:243], v[236:239], v[32:47]
	s_waitcnt lgkmcnt(1)
	v_mfma_f32_32x32x16_bf16 v[16:31], v[244:247], v[236:239], v[16:31]
	s_waitcnt lgkmcnt(0)
	v_mfma_f32_32x32x16_bf16 v[0:15], v[248:251], v[236:239], v[0:15]
	v_mov_b32_e32 v170, v234
	v_mov_b32_e32 v215, v162

.LBB0_205:
	s_add_i32 s17, s15, -1
	s_cmp_lt_u32 s17, s12
	s_cselect_b64 s[6:7], -1, 0
	s_and_b64 s[8:9], s[6:7], exec
	s_cselect_b32 s4, s17, s14
	s_lshl_b32 s4, s4, 6
	s_add_i32 s18, s15, -2
	s_or_b32 s19, s4, 32
	s_cmp_lt_u32 s18, s12
	s_cselect_b64 s[8:9], -1, 0
	v_mad_u64_u32 v[144:145], s[10:11], s4, v228, v[194:195]
	v_mad_u64_u32 v[148:149], s[10:11], s19, v228, v[194:195]
	s_and_b64 s[10:11], s[8:9], exec
	s_cselect_b32 s10, s18, s14
	s_lshl_b32 s10, s10, 6
	s_mov_b32 s11, s5
	v_lshl_add_u64 v[152:153], s[10:11], 1, v[196:197]
	v_add_co_u32_e32 v154, vcc, 0x80000, v152
	global_load_dwordx4 v[144:147], v[144:145], off
	s_nop 0
	global_load_dwordx4 v[148:151], v[148:149], off
	v_addc_co_u32_e32 v155, vcc, 0, v153, vcc
	global_load_dwordx4 v[156:159], v[152:153], off
	s_nop 0
	global_load_dwordx4 v[152:155], v[154:155], off
	s_sub_i32 s10, s13, 30
	v_cmp_le_u32_e32 vcc, s10, v212
	s_and_b64 s[10:11], s[8:9], vcc
	s_and_saveexec_b64 s[8:9], s[10:11]
	s_cbranch_execz .LBB0_207
	s_mul_i32 s10, s24, 0x4400
	v_add3_u32 v162, v203, s10, v204
	ds_read_b128 v[112:115], v162
	ds_read_b128 v[116:119], v162 offset:32
	ds_read_b128 v[120:123], v162 offset:64
	ds_read_b128 v[124:127], v162 offset:96
	ds_read_b128 v[222:225], v162 offset:8704
	ds_read_b128 v[236:239], v162 offset:8736
	ds_read_b128 v[240:243], v162 offset:8768
	ds_read_b128 v[244:247], v162 offset:8800
	s_waitcnt lgkmcnt(7)
	v_mfma_f32_32x32x16_bf16 v[96:111], v[112:115], v[128:131], 0
	s_waitcnt lgkmcnt(6)
	v_mfma_f32_32x32x16_bf16 v[96:111], v[116:119], v[132:135], v[96:111]
	s_waitcnt lgkmcnt(5)
	v_mfma_f32_32x32x16_bf16 v[96:111], v[120:123], v[136:139], v[96:111]
	s_waitcnt lgkmcnt(4)
	v_mfma_f32_32x32x16_bf16 v[96:111], v[124:127], v[140:143], v[96:111]
	s_waitcnt lgkmcnt(3)
	v_mfma_f32_32x32x16_bf16 v[112:127], v[222:225], v[128:131], 0
	s_waitcnt lgkmcnt(2)
	v_mfma_f32_32x32x16_bf16 v[112:127], v[236:239], v[132:135], v[112:127]
	s_waitcnt lgkmcnt(1)
	v_mfma_f32_32x32x16_bf16 v[112:127], v[240:243], v[136:139], v[112:127]
	s_waitcnt lgkmcnt(0)
	v_mfma_f32_32x32x16_bf16 v[112:127], v[244:247], v[140:143], v[112:127]

.LBB0_212:
	v_sub_f32_e32 v71, v71, v234
	v_sub_f32_e32 v70, v70, v234
	v_sub_f32_e32 v69, v69, v234
	v_sub_f32_e32 v68, v68, v234
	v_sub_f32_e32 v67, v67, v234
	v_sub_f32_e32 v66, v66, v234
	v_sub_f32_e32 v65, v65, v234
	v_sub_f32_e32 v64, v64, v234
	v_sub_f32_e32 v87, v87, v234
	v_sub_f32_e32 v86, v86, v234
	v_sub_f32_e32 v85, v85, v234
	v_sub_f32_e32 v84, v84, v234
	v_sub_f32_e32 v83, v83, v234
	v_sub_f32_e32 v82, v82, v234
	v_sub_f32_e32 v81, v81, v234
	v_sub_f32_e32 v80, v80, v234
	v_sub_f32_e32 v75, v75, v234
	v_sub_f32_e32 v74, v74, v234
	v_sub_f32_e32 v73, v73, v234
	v_sub_f32_e32 v72, v72, v234
	v_sub_f32_e32 v91, v91, v234
	v_sub_f32_e32 v90, v90, v234
	v_sub_f32_e32 v89, v89, v234
	v_sub_f32_e32 v88, v88, v234
	v_exp_f32_e32 v64, v64
	v_exp_f32_e32 v65, v65
	v_exp_f32_e32 v66, v66
	v_exp_f32_e32 v67, v67
	v_exp_f32_e32 v68, v68
	v_exp_f32_e32 v69, v69
	v_exp_f32_e32 v70, v70
	v_exp_f32_e32 v71, v71
	v_exp_f32_e32 v80, v80
	v_exp_f32_e32 v81, v81
	v_exp_f32_e32 v82, v82
	v_exp_f32_e32 v83, v83
	v_exp_f32_e32 v84, v84
	v_exp_f32_e32 v85, v85
	v_exp_f32_e32 v86, v86
	v_exp_f32_e32 v87, v87
	v_sub_f32_e32 v79, v79, v234
	v_sub_f32_e32 v78, v78, v234
	v_sub_f32_e32 v77, v77, v234
	v_sub_f32_e32 v76, v76, v234
	v_sub_f32_e32 v95, v95, v234
	v_sub_f32_e32 v94, v94, v234
	v_sub_f32_e32 v93, v93, v234
	v_sub_f32_e32 v92, v92, v234
	v_exp_f32_e32 v72, v72
	v_exp_f32_e32 v73, v73
	v_exp_f32_e32 v74, v74
	v_exp_f32_e32 v75, v75
	v_exp_f32_e32 v88, v88
	v_exp_f32_e32 v90, v90
	v_exp_f32_e32 v91, v91
	v_exp_f32_e32 v89, v89
	v_exp_f32_e32 v76, v76
	v_exp_f32_e32 v77, v77
	v_exp_f32_e32 v78, v78
	v_exp_f32_e32 v79, v79
	v_exp_f32_e32 v92, v92
	v_exp_f32_e32 v93, v93
	v_exp_f32_e32 v94, v94
	v_exp_f32_e32 v95, v95
	v_pk_add_f32 v[226:227], v[68:69], v[84:85]
	v_pk_add_f32 v[236:237], v[64:65], v[80:81]
	v_pk_add_f32 v[238:239], v[70:71], v[86:87]
	v_pk_add_f32 v[240:241], v[66:67], v[82:83]
	v_pk_add_f32 v[222:223], v[74:75], v[90:91]
	v_pk_add_f32 v[224:225], v[72:73], v[88:89]
	v_pk_add_f32 v[238:239], v[240:241], v[238:239]
	v_pk_add_f32 v[226:227], v[236:237], v[226:227]
	v_pk_add_f32 v[162:163], v[76:77], v[92:93]
	v_pk_add_f32 v[164:165], v[78:79], v[94:95]
	v_pk_add_f32 v[224:225], v[224:225], v[226:227]
	v_pk_add_f32 v[222:223], v[222:223], v[238:239]
	v_pk_add_f32 v[162:163], v[162:163], v[224:225]
	v_pk_add_f32 v[164:165], v[164:165], v[222:223]
	v_add_f32_e32 v162, v162, v163
	v_add_f32_e32 v163, v164, v165
	v_add_f32_e32 v162, v162, v163
	v_fmac_f32_e32 v162, v215, v170
	v_add_u32_e32 v163, v202, v169
	ds_read_b128 v[222:225], v163 offset:52224
	ds_read_b128 v[240:243], v163 offset:56832
	ds_read_b128 v[244:247], v163 offset:61440
	ds_read_b128 v[248:251], v207 offset:52224
	v_cvt_pk_bf16_f32 v236, v64, v65
	v_cvt_pk_bf16_f32 v237, v66, v67
	v_cvt_pk_bf16_f32 v238, v68, v69
	v_cvt_pk_bf16_f32 v239, v70, v71
	s_waitcnt lgkmcnt(3)
	s_nop 0
	v_mfma_f32_32x32x16_bf16 v[48:63], v[222:225], v[236:239], v[48:63]
	ds_read_b128 v[222:225], v163 offset:52256
	s_waitcnt lgkmcnt(3)
	v_mfma_f32_32x32x16_bf16 v[32:47], v[240:243], v[236:239], v[32:47]
	ds_read_b128 v[240:243], v163 offset:56864
	s_waitcnt lgkmcnt(3)
	v_mfma_f32_32x32x16_bf16 v[16:31], v[244:247], v[236:239], v[16:31]
	ds_read_b128 v[244:247], v163 offset:61472
	s_waitcnt lgkmcnt(3)
	v_mfma_f32_32x32x16_bf16 v[0:15], v[248:251], v[236:239], v[0:15]
	ds_read_b128 v[248:251], v207 offset:52256
	v_cvt_pk_bf16_f32 v236, v72, v73
	v_cvt_pk_bf16_f32 v237, v74, v75
	v_cvt_pk_bf16_f32 v238, v76, v77
	v_cvt_pk_bf16_f32 v239, v78, v79
	s_waitcnt lgkmcnt(3)
	s_nop 0
	v_mfma_f32_32x32x16_bf16 v[48:63], v[222:225], v[236:239], v[48:63]
	ds_read_b128 v[222:225], v163 offset:52288
	s_waitcnt lgkmcnt(3)
	v_mfma_f32_32x32x16_bf16 v[32:47], v[240:243], v[236:239], v[32:47]
	ds_read_b128 v[240:243], v163 offset:56896
	s_waitcnt lgkmcnt(3)
	v_mfma_f32_32x32x16_bf16 v[16:31], v[244:247], v[236:239], v[16:31]
	ds_read_b128 v[244:247], v163 offset:61504
	s_waitcnt lgkmcnt(3)
	v_mfma_f32_32x32x16_bf16 v[0:15], v[248:251], v[236:239], v[0:15]
	ds_read_b128 v[248:251], v207 offset:52288
	v_cvt_pk_bf16_f32 v236, v80, v81
	v_cvt_pk_bf16_f32 v237, v82, v83
	v_cvt_pk_bf16_f32 v238, v84, v85
	v_cvt_pk_bf16_f32 v239, v86, v87
	s_waitcnt lgkmcnt(3)
	s_nop 0
	v_mfma_f32_32x32x16_bf16 v[48:63], v[222:225], v[236:239], v[48:63]
	ds_read_b128 v[222:225], v163 offset:52320
	s_waitcnt lgkmcnt(3)
	v_mfma_f32_32x32x16_bf16 v[32:47], v[240:243], v[236:239], v[32:47]
	ds_read_b128 v[240:243], v163 offset:56928
	s_waitcnt lgkmcnt(3)
	v_mfma_f32_32x32x16_bf16 v[16:31], v[244:247], v[236:239], v[16:31]
	ds_read_b128 v[244:247], v163 offset:61536
	s_waitcnt lgkmcnt(3)
	v_mfma_f32_32x32x16_bf16 v[0:15], v[248:251], v[236:239], v[0:15]
	ds_read_b128 v[248:251], v207 offset:52320
	v_cvt_pk_bf16_f32 v236, v88, v89
	v_cvt_pk_bf16_f32 v237, v90, v91
	v_cvt_pk_bf16_f32 v238, v92, v93
	v_cvt_pk_bf16_f32 v239, v94, v95
	s_waitcnt lgkmcnt(3)
	s_nop 0
	v_mfma_f32_32x32x16_bf16 v[48:63], v[222:225], v[236:239], v[48:63]
	s_waitcnt lgkmcnt(2)
	v_mfma_f32_32x32x16_bf16 v[32:47], v[240:243], v[236:239], v[32:47]
	s_waitcnt lgkmcnt(1)
	v_mfma_f32_32x32x16_bf16 v[16:31], v[244:247], v[236:239], v[16:31]
	s_waitcnt lgkmcnt(0)
	v_mfma_f32_32x32x16_bf16 v[0:15], v[248:251], v[236:239], v[0:15]
	v_mov_b32_e32 v170, v234
	v_mov_b32_e32 v215, v162
.LBB0_213:
	s_or_b64 exec, exec, s[8:9]
	s_mul_i32 s8, s16, 0x4400
	v_add_u32_e32 v162, s8, v175
	s_cmp_lt_u32 s15, s12
	s_waitcnt vmcnt(3)
	ds_write_b128 v162, v[144:147]
	s_waitcnt vmcnt(2)
	ds_write_b128 v162, v[148:151] offset:8704
	s_waitcnt vmcnt(1)
	ds_write2_b64 v208, v[156:157], v[158:159] offset1:2
	v_add_u32_e32 v144, 0x2000, v208
	s_cselect_b32 s9, s15, s14
	s_waitcnt vmcnt(0)
	ds_write2_b64 v144, v[152:153], v[154:155] offset0:128 offset1:130
	s_lshl_b32 s9, s9, 6
	v_lshl_add_u64 v[152:153], s[4:5], 1, v[196:197]
	v_mad_u64_u32 v[144:145], s[10:11], s9, v228, v[194:195]
	s_or_b32 s9, s9, 32
	v_add_co_u32_e32 v154, vcc, 0x80000, v152
	v_mad_u64_u32 v[148:149], s[10:11], s9, v228, v[194:195]
	s_nop 0
	v_addc_co_u32_e32 v155, vcc, 0, v153, vcc
	s_waitcnt lgkmcnt(0)
	s_barrier
	global_load_dwordx4 v[144:147], v[144:145], off
	s_nop 0
	global_load_dwordx4 v[148:151], v[148:149], off
	s_nop 0
	global_load_dwordx4 v[156:159], v[152:153], off
	s_nop 0
	global_load_dwordx4 v[152:155], v[154:155], off
	s_add_i32 s4, s13, 34
	v_cmp_le_u32_e32 vcc, s4, v212
	s_and_b64 s[10:11], s[6:7], vcc
	s_and_saveexec_b64 s[6:7], s[10:11]
	s_cbranch_execz .LBB0_215
	v_add3_u32 v162, v203, s8, v204
	ds_read_b128 v[80:83], v162
	ds_read_b128 v[84:87], v162 offset:32
	ds_read_b128 v[88:91], v162 offset:64
	ds_read_b128 v[92:95], v162 offset:96
	ds_read_b128 v[222:225], v162 offset:8704
	ds_read_b128 v[236:239], v162 offset:8736
	ds_read_b128 v[240:243], v162 offset:8768
	ds_read_b128 v[244:247], v162 offset:8800
	s_waitcnt lgkmcnt(7)
	v_mfma_f32_32x32x16_bf16 v[64:79], v[80:83], v[128:131], 0
	s_waitcnt lgkmcnt(6)
	v_mfma_f32_32x32x16_bf16 v[64:79], v[84:87], v[132:135], v[64:79]
	s_waitcnt lgkmcnt(5)
	v_mfma_f32_32x32x16_bf16 v[64:79], v[88:91], v[136:139], v[64:79]
	s_waitcnt lgkmcnt(4)
	v_mfma_f32_32x32x16_bf16 v[64:79], v[92:95], v[140:143], v[64:79]
	s_waitcnt lgkmcnt(3)
	v_mfma_f32_32x32x16_bf16 v[80:95], v[222:225], v[128:131], 0
	s_waitcnt lgkmcnt(2)
	v_mfma_f32_32x32x16_bf16 v[80:95], v[236:239], v[132:135], v[80:95]
	s_waitcnt lgkmcnt(1)
	v_mfma_f32_32x32x16_bf16 v[80:95], v[240:243], v[136:139], v[80:95]
	s_waitcnt lgkmcnt(0)
	v_mfma_f32_32x32x16_bf16 v[80:95], v[244:247], v[140:143], v[80:95]

.LBB0_220:
	s_setprio 0
	ds_bpermute_b32 v64, v173, v215
	s_waitcnt lgkmcnt(0)
	v_add_f32_e32 v64, v215, v64
	v_div_scale_f32 v65, s[6:7], v64, v64, 1.0
	v_rcp_f32_e32 v66, v65
	v_div_scale_f32 v67, vcc, 1.0, v64, 1.0
	v_fma_f32 v68, -v65, v66, 1.0
	v_fmac_f32_e32 v66, v68, v66
	v_mul_f32_e32 v68, v67, v66
	v_fma_f32 v69, -v65, v68, v67
	v_fmac_f32_e32 v68, v69, v66
	v_fma_f32 v65, -v65, v68, v67
	v_div_fmas_f32 v65, v65, v66, v68
	v_div_fixup_f32 v70, v65, v64, 1.0
	s_and_saveexec_b64 s[6:7], s[38:39]
	s_cbranch_execz .LBB0_222
	v_mul_f32_e32 v64, v48, v70
	v_mul_f32_e32 v65, v49, v70
	ds_write2st64_b32 v205, v64, v65 offset1:1
	v_mul_f32_e32 v64, v50, v70
	v_mul_f32_e32 v65, v51, v70
	ds_write2st64_b32 v205, v64, v65 offset0:2 offset1:3
	v_mul_f32_e32 v64, v52, v70
	v_mul_f32_e32 v65, v53, v70
	ds_write2st64_b32 v205, v64, v65 offset0:4 offset1:5
	v_mul_f32_e32 v64, v54, v70
	v_mul_f32_e32 v65, v55, v70
	ds_write2st64_b32 v205, v64, v65 offset0:6 offset1:7
	v_mul_f32_e32 v64, v56, v70
	v_mul_f32_e32 v65, v57, v70
	ds_write2st64_b32 v205, v64, v65 offset0:8 offset1:9
	v_mul_f32_e32 v64, v58, v70
	v_mul_f32_e32 v65, v59, v70
	ds_write2st64_b32 v205, v64, v65 offset0:10 offset1:11
	v_mul_f32_e32 v64, v60, v70
	v_mul_f32_e32 v65, v61, v70
	ds_write2st64_b32 v205, v64, v65 offset0:12 offset1:13
	v_mul_f32_e32 v64, v62, v70
	v_mul_f32_e32 v65, v63, v70
	ds_write2st64_b32 v205, v64, v65 offset0:14 offset1:15
	v_mul_f32_e32 v64, v32, v70
	v_mul_f32_e32 v65, v33, v70
	ds_write2st64_b32 v205, v64, v65 offset0:16 offset1:17
	v_mul_f32_e32 v64, v34, v70
	v_mul_f32_e32 v65, v35, v70
	ds_write2st64_b32 v205, v64, v65 offset0:18 offset1:19
	v_mul_f32_e32 v64, v36, v70
	v_mul_f32_e32 v65, v37, v70
	ds_write2st64_b32 v205, v64, v65 offset0:20 offset1:21
	v_mul_f32_e32 v64, v38, v70
	v_mul_f32_e32 v65, v39, v70
	ds_write2st64_b32 v205, v64, v65 offset0:22 offset1:23
	v_mul_f32_e32 v64, v40, v70
	v_mul_f32_e32 v65, v41, v70
	ds_write2st64_b32 v205, v64, v65 offset0:24 offset1:25
	v_mul_f32_e32 v64, v42, v70
	v_mul_f32_e32 v65, v43, v70
	ds_write2st64_b32 v205, v64, v65 offset0:26 offset1:27
	v_mul_f32_e32 v64, v44, v70
	v_mul_f32_e32 v65, v45, v70
	ds_write2st64_b32 v205, v64, v65 offset0:28 offset1:29
	v_mul_f32_e32 v64, v46, v70
	v_mul_f32_e32 v65, v47, v70
	ds_write2st64_b32 v205, v64, v65 offset0:30 offset1:31
	v_mul_f32_e32 v64, v16, v70
	v_mul_f32_e32 v65, v17, v70
	ds_write2st64_b32 v205, v64, v65 offset0:32 offset1:33
	v_mul_f32_e32 v64, v18, v70
	v_mul_f32_e32 v65, v19, v70
	ds_write2st64_b32 v205, v64, v65 offset0:34 offset1:35
	v_mul_f32_e32 v64, v20, v70
	v_mul_f32_e32 v65, v21, v70
	ds_write2st64_b32 v205, v64, v65 offset0:36 offset1:37
	v_mul_f32_e32 v64, v22, v70
	v_mul_f32_e32 v65, v23, v70
	ds_write2st64_b32 v205, v64, v65 offset0:38 offset1:39
	v_mul_f32_e32 v64, v24, v70
	v_mul_f32_e32 v65, v25, v70
	ds_write2st64_b32 v205, v64, v65 offset0:40 offset1:41
	v_mul_f32_e32 v64, v26, v70
	v_mul_f32_e32 v65, v27, v70
	ds_write2st64_b32 v205, v64, v65 offset0:42 offset1:43
	v_mul_f32_e32 v64, v28, v70
	v_mul_f32_e32 v65, v29, v70
	ds_write2st64_b32 v205, v64, v65 offset0:44 offset1:45
	v_mul_f32_e32 v64, v30, v70
	v_mul_f32_e32 v65, v31, v70
	ds_write2st64_b32 v205, v64, v65 offset0:46 offset1:47
	v_mul_f32_e32 v64, v0, v70
	v_mul_f32_e32 v65, v1, v70
	ds_write2st64_b32 v205, v64, v65 offset0:48 offset1:49
	v_mul_f32_e32 v64, v2, v70
	v_mul_f32_e32 v65, v3, v70
	ds_write2st64_b32 v205, v64, v65 offset0:50 offset1:51
	v_mul_f32_e32 v64, v4, v70
	v_mul_f32_e32 v65, v5, v70
	ds_write2st64_b32 v205, v64, v65 offset0:52 offset1:53
	v_mul_f32_e32 v64, v6, v70
	v_mul_f32_e32 v65, v7, v70
	ds_write2st64_b32 v205, v64, v65 offset0:54 offset1:55
	v_mul_f32_e32 v64, v8, v70
	v_mul_f32_e32 v65, v9, v70
	ds_write2st64_b32 v205, v64, v65 offset0:56 offset1:57
	v_mul_f32_e32 v64, v10, v70
	v_mul_f32_e32 v65, v11, v70
	ds_write2st64_b32 v205, v64, v65 offset0:58 offset1:59
	v_mul_f32_e32 v64, v12, v70
	v_mul_f32_e32 v65, v13, v70
	ds_write2st64_b32 v205, v64, v65 offset0:60 offset1:61
	v_mul_f32_e32 v64, v14, v70
	v_mul_f32_e32 v65, v15, v70
	ds_write2st64_b32 v205, v64, v65 offset0:62 offset1:63
